# MLA: three DMA pieces issued in the vector block, the fourth at the start of the matrix block
# baseline (speedup 1.0000x reference)
; DI unsigned pk2(float lo, float hi) { const f32x2_t v = {lo, hi}; const bf16x2_t b = __builtin_convertvector(v, bf16x2_t); return __builtin_bit_cast(unsigned, b); }
; #define MLA_DMA(t, slot) do { _Pragma("unroll") for (int i_ = 0; i_ < 4; ++i_) { const bf16_t* src_ = (pisk[i_] ? kbase : vbase) + poff[i_] + (size_t)(t) * pstep[i_]; \
;         __builtin_amdgcn_global_load_lds((const unsigned*)src_, (LAS unsigned*)(lds + (slot) * SLOT + (w + 8 * i_) * 1024), 16, 0, 0); } } while (0)
; DI void mla_attn_phase(LAS unsigned char* lds, const bf16_t* Qg, const bf16_t* Kg, const bf16_t* Vtg, bf16_t* MIX) {
;     ...
;                 if (kt + 2 < NT) MLA_DMA(kt + 2, sl2);
;     ...
;                     const float m_new = fmaxf(m_run, mx), alpha = __builtin_amdgcn_exp2f(m_run - m_new); m_run = m_new;
;                     float sum = 0.f;
; #pragma unroll
;                     for (int i = 0; i < 16; ++i) { s0[i] = __builtin_amdgcn_exp2f(s0[i] - m_new); s1[i] = __builtin_amdgcn_exp2f(s1[i] - m_new); sum += s0[i] + s1[i]; }
;                     l_run = l_run * alpha + sum;
;                     if (__any(alpha != 1.f)) {
; #pragma unroll
;                         for (int mt = 0; mt < 4; ++mt)
; #pragma unroll
;                             for (int i = 0; i < 16; ++i) o[mt][i] *= alpha; }
;                     bf16x8 pf[4];
; #pragma unroll
;                     for (int sp = 0; sp < 2; ++sp) { u32x4 p0, p1;
; #pragma unroll
;                         for (int j = 0; j < 4; ++j) { p0[j] = pk2(s0[8 * sp + 2 * j], s0[8 * sp + 2 * j + 1]); p1[j] = pk2(s1[8 * sp + 2 * j], s1[8 * sp + 2 * j + 1]); }
;                         pf[sp] = __builtin_bit_cast(bf16x8, p0); pf[2 + sp] = __builtin_bit_cast(bf16x8, p1); }
.Lmla_nodma:
	v_lshl_add_u64 v[214:215], v[214:215], 0, s[20:21]
	v_lshl_add_u64 v[212:213], v[212:213], 0, s[2:3]
	v_lshl_add_u64 v[210:211], v[210:211], 0, s[22:23]
	s_cmp_gt_i32 s40, s39
	s_cbranch_scc1 .Lmla_x
	v_sub_f32_e32 v80, v80, v3
	v_sub_f32_e32 v96, v96, v3
	v_exp_f32_e32 v80, v80
	v_exp_f32_e32 v96, v96
	v_sub_f32_e32 v81, v81, v3
	v_sub_f32_e32 v97, v97, v3
	v_exp_f32_e32 v81, v81
	v_exp_f32_e32 v97, v97
	v_sub_f32_e32 v82, v82, v3
	v_sub_f32_e32 v98, v98, v3
	v_exp_f32_e32 v82, v82
	v_exp_f32_e32 v98, v98
	v_sub_f32_e32 v83, v83, v3
	v_sub_f32_e32 v99, v99, v3
	v_exp_f32_e32 v83, v83
	v_exp_f32_e32 v99, v99
	v_add_f32_e32 v218, v80, v96
	v_sub_f32_e32 v84, v84, v3
	v_add_f32_e32 v218, 0, v218
	v_add_f32_e32 v219, v81, v97
	v_exp_f32_e32 v226, v84
	v_sub_f32_e32 v84, v100, v3
	v_add_f32_e32 v218, v219, v218
	v_add_f32_e32 v219, v82, v98
	v_exp_f32_e32 v100, v84
	v_sub_f32_e32 v84, v85, v3
	v_add_f32_e32 v218, v219, v218
	v_add_f32_e32 v219, v83, v99
	v_exp_f32_e32 v227, v84
	v_sub_f32_e32 v84, v101, v3
	v_sub_f32_e32 v86, v86, v3
	v_exp_f32_e32 v101, v84
	v_add_f32_e32 v84, v219, v218
	v_exp_f32_e32 v218, v86
	v_sub_f32_e32 v86, v102, v3
	v_exp_f32_e32 v102, v86
	v_sub_f32_e32 v86, v87, v3
	v_exp_f32_e32 v87, v86
	v_sub_f32_e32 v86, v103, v3
	v_exp_f32_e32 v103, v86
	v_sub_f32_e32 v86, v88, v3
	v_exp_f32_e32 v88, v86
	v_sub_f32_e32 v86, v104, v3
	v_exp_f32_e32 v104, v86
	v_sub_f32_e32 v86, v89, v3
	v_exp_f32_e32 v89, v86
	v_sub_f32_e32 v86, v105, v3
	v_exp_f32_e32 v105, v86
	v_sub_f32_e32 v86, v90, v3
	v_exp_f32_e32 v90, v86
	v_sub_f32_e32 v86, v106, v3
	v_exp_f32_e32 v106, v86
	v_sub_f32_e32 v86, v91, v3
	v_exp_f32_e32 v91, v86
	v_sub_f32_e32 v86, v107, v3
	v_exp_f32_e32 v107, v86
	v_sub_f32_e32 v86, v92, v3
	v_add_f32_e32 v85, v226, v100
	v_exp_f32_e32 v219, v86
	v_sub_f32_e32 v86, v108, v3
	v_add_f32_e32 v84, v85, v84
	v_add_f32_e32 v85, v227, v101
	v_exp_f32_e32 v108, v86
	v_sub_f32_e32 v86, v93, v3
	v_add_f32_e32 v84, v85, v84
	v_add_f32_e32 v85, v218, v102
	v_exp_f32_e32 v234, v86
	v_sub_f32_e32 v86, v109, v3
	v_add_f32_e32 v84, v85, v84
	v_add_f32_e32 v85, v87, v103
	v_exp_f32_e32 v109, v86
	v_sub_f32_e32 v86, v94, v3
	v_add_f32_e32 v84, v85, v84
	v_add_f32_e32 v85, v88, v104
	v_exp_f32_e32 v235, v86
	v_sub_f32_e32 v86, v110, v3
	v_add_f32_e32 v84, v85, v84
	v_add_f32_e32 v85, v89, v105
	v_exp_f32_e32 v110, v86
	v_sub_f32_e32 v86, v95, v3
	v_add_f32_e32 v84, v85, v84
	v_add_f32_e32 v85, v90, v106
	v_exp_f32_e32 v95, v86
	v_sub_f32_e32 v86, v111, v3
	v_add_f32_e32 v84, v85, v84
	v_add_f32_e32 v85, v91, v107
	v_exp_f32_e32 v111, v86
	v_add_f32_e32 v84, v85, v84
	v_add_f32_e32 v85, v219, v108
	v_add_f32_e32 v84, v85, v84
	v_add_f32_e32 v85, v234, v109
	v_add_f32_e32 v84, v85, v84
	v_add_f32_e32 v85, v235, v110
	v_add_f32_e32 v84, v85, v84
	v_add_f32_e32 v85, v95, v111
	v_add_f32_e32 v236, v85, v84
	v_fmac_f32_e32 v236, v233, v0
	v_cvt_pk_bf16_f32 v80, v80, v81
	v_cvt_pk_bf16_f32 v84, v96, v97
	v_cvt_pk_bf16_f32 v81, v82, v83
	v_cvt_pk_bf16_f32 v85, v98, v99
	v_cvt_pk_bf16_f32 v82, v226, v227
	v_cvt_pk_bf16_f32 v86, v100, v101
	v_cvt_pk_bf16_f32 v83, v218, v87
	v_cvt_pk_bf16_f32 v87, v102, v103
	v_cvt_pk_bf16_f32 v88, v88, v89
	v_cvt_pk_bf16_f32 v92, v104, v105
	v_cvt_pk_bf16_f32 v89, v90, v91
	v_cvt_pk_bf16_f32 v93, v106, v107
	v_cvt_pk_bf16_f32 v90, v219, v234
	v_cvt_pk_bf16_f32 v94, v108, v109
	v_cvt_pk_bf16_f32 v91, v235, v95
	v_cvt_pk_bf16_f32 v95, v110, v111
.Lmla_x:
	s_cmp_lt_u32 s34, 0x80
	s_cbranch_scc0 .Lmla_xb
	s_add_i32 s30, s42, 2
	s_cmp_ge_i32 s30, s38
	s_cbranch_scc1 .Lmla_xw0
	s_waitcnt vmcnt(3)
	s_branch .Lmla_xb

; #define MLA_DMA(t, slot) do { _Pragma("unroll") for (int i_ = 0; i_ < 4; ++i_) { const bf16_t* src_ = (pisk[i_] ? kbase : vbase) + poff[i_] + (size_t)(t) * pstep[i_]; \
;         __builtin_amdgcn_global_load_lds((const unsigned*)src_, (LAS unsigned*)(lds + (slot) * SLOT + (w + 8 * i_) * 1024), 16, 0, 0); } } while (0)
; DI void mla_attn_phase(LAS unsigned char* lds, const bf16_t* Qg, const bf16_t* Kg, const bf16_t* Vtg, bf16_t* MIX) {
;     ...
;                 if (kt + 2 < NT) MLA_DMA(kt + 2, sl2);
.Lmla_xb:
	s_barrier
	s_and_b64 vcc, exec, s[28:29]
	s_cbranch_vccnz .Lmla_nodma2
	s_add_i32 m0, s31, 0x6000
	s_nop 0
	global_load_lds_dwordx4 v[216:217], off
.Lmla_nodma2:
	v_lshl_add_u64 v[216:217], v[216:217], 0, s[18:19]
	s_cmp_gt_i32 s40, s39
	s_cbranch_scc1 .LBB0_367
	s_waitcnt lgkmcnt(6)
	v_mfma_f32_32x32x16_bf16 v[64:79], v[144:147], v[80:83], v[64:79]
	v_mfma_f32_32x32x16_bf16 v[48:63], v[140:143], v[80:83], v[48:63]
	s_waitcnt lgkmcnt(0)
	v_mfma_f32_32x32x16_bf16 v[32:47], v[148:151], v[80:83], v[32:47]
	v_mfma_f32_32x32x16_bf16 v[16:31], v[152:155], v[80:83], v[16:31]
	ds_read_b128 v[80:83], v1 offset:13376
	ds_read_b128 v[96:99], v1 offset:17984
	ds_read_b128 v[100:103], v1 offset:22592
	ds_read_b128 v[104:107], v1 offset:27200
	v_mfma_f32_32x32x16_bf16 v[64:79], v[136:139], v[88:91], v[64:79]
	v_mfma_f32_32x32x16_bf16 v[48:63], v[12:15], v[88:91], v[48:63]
	v_mfma_f32_32x32x16_bf16 v[32:47], v[4:7], v[88:91], v[32:47]
	v_mfma_f32_32x32x16_bf16 v[16:31], v[8:11], v[88:91], v[16:31]
	ds_read_b128 v[4:7], v1 offset:13408
	ds_read_b128 v[8:11], v1 offset:18016
	ds_read_b128 v[12:15], v1 offset:22624
	ds_read_b128 v[88:91], v1 offset:27232
	s_waitcnt lgkmcnt(4)
	v_mfma_f32_32x32x16_bf16 v[64:79], v[80:83], v[84:87], v[64:79]
	v_mov_b32_e32 v233, v236
	v_mfma_f32_32x32x16_bf16 v[48:63], v[96:99], v[84:87], v[48:63]
	v_mfma_f32_32x32x16_bf16 v[32:47], v[100:103], v[84:87], v[32:47]
	v_mfma_f32_32x32x16_bf16 v[16:31], v[104:107], v[84:87], v[16:31]
	s_waitcnt lgkmcnt(0)
	v_mfma_f32_32x32x16_bf16 v[64:79], v[4:7], v[92:95], v[64:79]
	v_mfma_f32_32x32x16_bf16 v[48:63], v[8:11], v[92:95], v[48:63]
	v_mfma_f32_32x32x16_bf16 v[32:47], v[12:15], v[92:95], v[32:47]
	v_mfma_f32_32x32x16_bf16 v[16:31], v[88:91], v[92:95], v[16:31]
	s_branch .LBB0_371
